# P5 no-rs epilogue: the vmcnt(0) that drained the next unit's LDS-DMA prefetch at epilogue start and the dead rs computation are removed
# baseline (speedup 1.0000x reference)
; __device__ __forceinline__ size_t tm_block(int pm, int ct, int nct) { return ((size_t)pm * nct + ct) * 32768; }
; __device__ __forceinline__ u32x4 pack8(const f32x4& v0, const f32x4& v1) { u32x4 w; w.x = cvt_pk_bf16(v0[0], v0[1]); w.y = cvt_pk_bf16(v0[2], v0[3]); w.z = cvt_pk_bf16(v1[0], v1[1]); w.w = cvt_pk_bf16(v1[2], v1[3]); return w; }
;     __device__ __forceinline__ void post(const f32x4 (&acc)[2][2][4][2], const float (&st)[8], const Unit& u, int wr, int wc, int fr, int fq) const {
;         const PieceOut po(scr, O, tm_block(u.pm, u.pn * 4 + wc, 64), wr, wc, fr, fq);
; #pragma unroll
;         for (int ai = 0; ai < 2; ++ai)
; #pragma unroll
;             for (int m = 0; m < 4; ++m) { const float rs = __builtin_amdgcn_rsqf(st[ai * 4 + m] * (1.0f / 1024.0f) + eps);
; #pragma unroll
;                 for (int bj = 0; bj < 2; ++bj) { f32x4 v0 = acc[ai][bj][m][0] * rs, v1 = acc[ai][bj][m][1] * rs;
; #pragma unroll
;                     for (int k = 0; k < 4; ++k) { const float a = fmaxf(v0[k], 0.f), b = fmaxf(v1[k], 0.f); v0[k] = a * a; v1[k] = b * b; }
;                     po.put(bj, pack8(v0, v1)); }
;                 po.flush<true>(ai, m); }
;     }
.Lp5_epi_nors:
	s_lshl_b32 s17, s25, 2
	s_or_b32 s26, s17, s48
	s_ashr_i32 s25, s24, 31
	v_max_f32_e32 v122, 0, v122
	v_mul_f32_e32 v165, v122, v122
	v_max_f32_e32 v122, 0, v127
	v_max_f32_e32 v123, 0, v123
	v_max_f32_e32 v124, 0, v124
	v_max_f32_e32 v126, 0, v126
	v_mul_f32_e32 v122, v122, v122
	v_mul_f32_e32 v127, v123, v123
	v_max_f32_e32 v123, 0, v128
	v_mul_f32_e32 v128, v124, v124
	v_max_f32_e32 v124, 0, v129
	v_max_f32_e32 v125, 0, v125
	v_mul_f32_e32 v126, v126, v126
	v_mul_f32_e32 v123, v123, v123
	v_mul_f32_e32 v124, v124, v124
	v_mul_f32_e32 v125, v125, v125
	v_cvt_pk_bf16_f32 v122, v126, v122
	v_max_f32_e32 v114, 0, v114
	v_cvt_pk_bf16_f32 v123, v123, v124
	v_cvt_pk_bf16_f32 v124, v165, v127
	v_cvt_pk_bf16_f32 v125, v128, v125
	ds_write_b128 v157, v[122:125]
	v_mul_f32_e32 v122, v114, v114
	v_max_f32_e32 v114, 0, v119
	v_max_f32_e32 v115, 0, v115
	v_max_f32_e32 v116, 0, v116
	s_ashr_i32 s27, s26, 31
	v_max_f32_e32 v118, 0, v118
	v_mul_f32_e32 v114, v114, v114
	v_mul_f32_e32 v119, v115, v115
	v_max_f32_e32 v115, 0, v120
	v_mul_f32_e32 v120, v116, v116
	v_max_f32_e32 v116, 0, v121
	v_max_f32_e32 v117, 0, v117
	s_lshl_b64 s[24:25], s[24:25], 21
	s_lshl_b64 s[26:27], s[26:27], 15
	v_mul_f32_e32 v118, v118, v118
	v_mul_f32_e32 v115, v115, v115
	v_mul_f32_e32 v116, v116, v116
	v_mul_f32_e32 v117, v117, v117
	v_cvt_pk_bf16_f32 v114, v118, v114
	s_add_u32 s17, s38, s24
	v_cvt_pk_bf16_f32 v115, v115, v116
	v_cvt_pk_bf16_f32 v116, v122, v119
	v_cvt_pk_bf16_f32 v117, v120, v117
	ds_write_b128 v157, v[114:117] offset:64
	s_addc_u32 s19, s39, s25
	s_add_u32 s17, s17, s26
	ds_read_b128 v[116:119], v158
	ds_read_b128 v[120:123], v158 offset:1152
	s_addc_u32 s19, s19, s27
	s_add_u32 s24, s17, s14
	s_addc_u32 s25, s19, s15
	v_lshl_add_u64 v[114:115], s[24:25], 0, v[138:139]
	v_max_f32_e32 v106, 0, v106
	s_waitcnt lgkmcnt(1)
	global_store_dwordx4 v[114:115], v[116:119], off nt
	s_waitcnt lgkmcnt(0)
	global_store_dwordx4 v[114:115], v[120:123], off offset:1024 nt
	v_mul_f32_e32 v116, v106, v106
	v_max_f32_e32 v106, 0, v111
	v_max_f32_e32 v107, 0, v107
	v_max_f32_e32 v108, 0, v108
	v_max_f32_e32 v110, 0, v110
	v_mul_f32_e32 v106, v106, v106
	v_mul_f32_e32 v111, v107, v107
	v_max_f32_e32 v107, 0, v112
	v_mul_f32_e32 v112, v108, v108
	v_max_f32_e32 v108, 0, v113
	v_max_f32_e32 v109, 0, v109
	v_mul_f32_e32 v110, v110, v110
	v_mul_f32_e32 v107, v107, v107
	v_mul_f32_e32 v108, v108, v108
	v_mul_f32_e32 v109, v109, v109
	v_cvt_pk_bf16_f32 v106, v110, v106
	v_max_f32_e32 v98, 0, v98
	v_max_f32_e32 v99, 0, v99
	v_max_f32_e32 v100, 0, v100
	v_cvt_pk_bf16_f32 v107, v107, v108
	v_cvt_pk_bf16_f32 v108, v116, v111
	v_cvt_pk_bf16_f32 v109, v112, v109
	ds_write_b128 v157, v[106:109]
	v_mul_f32_e32 v106, v98, v98
	v_max_f32_e32 v98, 0, v103
	v_mul_f32_e32 v103, v99, v99
	v_max_f32_e32 v99, 0, v104
	v_mul_f32_e32 v104, v100, v100
	v_max_f32_e32 v100, 0, v105
	v_max_f32_e32 v102, 0, v102
	v_mul_f32_e32 v98, v98, v98
	v_mul_f32_e32 v99, v99, v99
	v_max_f32_e32 v101, 0, v101
	v_mul_f32_e32 v100, v100, v100
	v_mul_f32_e32 v102, v102, v102
	v_mul_f32_e32 v101, v101, v101
	v_cvt_pk_bf16_f32 v98, v102, v98
	v_cvt_pk_bf16_f32 v99, v99, v100
	v_cvt_pk_bf16_f32 v100, v106, v103
	v_cvt_pk_bf16_f32 v101, v104, v101
	ds_write_b128 v157, v[98:101] offset:64
	ds_read_b128 v[98:101], v158
	ds_read_b128 v[102:105], v158 offset:1152
	s_waitcnt lgkmcnt(1)
	global_store_dwordx4 v[114:115], v[98:101], off offset:2048 nt
	s_waitcnt lgkmcnt(0)
	global_store_dwordx4 v[114:115], v[102:105], off offset:3072 nt
	v_max_f32_e32 v90, 0, v90
	v_mul_f32_e32 v98, v90, v90
	v_max_f32_e32 v90, 0, v95
	v_max_f32_e32 v91, 0, v91
	v_max_f32_e32 v92, 0, v92
	v_max_f32_e32 v94, 0, v94
	v_mul_f32_e32 v90, v90, v90
	v_mul_f32_e32 v95, v91, v91
	v_max_f32_e32 v91, 0, v96
	v_mul_f32_e32 v96, v92, v92
	v_max_f32_e32 v92, 0, v97
	v_max_f32_e32 v93, 0, v93
	v_mul_f32_e32 v94, v94, v94
	v_mul_f32_e32 v91, v91, v91
	v_mul_f32_e32 v92, v92, v92
	v_mul_f32_e32 v93, v93, v93
	v_cvt_pk_bf16_f32 v90, v94, v90
	v_max_f32_e32 v82, 0, v82
	v_max_f32_e32 v83, 0, v83
	v_max_f32_e32 v84, 0, v84
	v_cvt_pk_bf16_f32 v91, v91, v92
	v_cvt_pk_bf16_f32 v92, v98, v95
	v_cvt_pk_bf16_f32 v93, v96, v93
	ds_write_b128 v157, v[90:93]
	v_mul_f32_e32 v90, v82, v82
	v_max_f32_e32 v82, 0, v87
	v_mul_f32_e32 v87, v83, v83
	v_max_f32_e32 v83, 0, v88
	v_mul_f32_e32 v88, v84, v84
	v_max_f32_e32 v84, 0, v89
	v_max_f32_e32 v86, 0, v86
	v_mul_f32_e32 v82, v82, v82
	v_mul_f32_e32 v83, v83, v83
	v_max_f32_e32 v85, 0, v85
	v_mul_f32_e32 v84, v84, v84
	v_mul_f32_e32 v86, v86, v86
	v_mul_f32_e32 v85, v85, v85
	v_cvt_pk_bf16_f32 v82, v86, v82
	v_cvt_pk_bf16_f32 v83, v83, v84
	v_cvt_pk_bf16_f32 v84, v90, v87
	v_cvt_pk_bf16_f32 v85, v88, v85
	ds_write_b128 v157, v[82:85] offset:64
	ds_read_b128 v[82:85], v158
	ds_read_b128 v[86:89], v158 offset:1152
	v_add_co_u32_e32 v92, vcc, s53, v114
	s_nop 0
	s_nop 0
	v_addc_co_u32_e32 v93, vcc, 0, v115, vcc
	v_max_f32_e32 v74, 0, v74
	s_waitcnt lgkmcnt(1)
	global_store_dwordx4 v[92:93], v[82:85], off nt
	s_waitcnt lgkmcnt(0)
; __device__ __forceinline__ size_t tm_block(int pm, int ct, int nct) { return ((size_t)pm * nct + ct) * 32768; }
; __device__ __forceinline__ u32x4 pack8(const f32x4& v0, const f32x4& v1) { u32x4 w; w.x = cvt_pk_bf16(v0[0], v0[1]); w.y = cvt_pk_bf16(v0[2], v0[3]); w.z = cvt_pk_bf16(v1[0], v1[1]); w.w = cvt_pk_bf16(v1[2], v1[3]); return w; }
;     __device__ __forceinline__ void post(const f32x4 (&acc)[2][2][4][2], const float (&st)[8], const Unit& u, int wr, int wc, int fr, int fq) const {
;         const PieceOut po(scr, O, tm_block(u.pm, u.pn * 4 + wc, 64), wr, wc, fr, fq);
; #pragma unroll
;         for (int ai = 0; ai < 2; ++ai)
; #pragma unroll
;             for (int m = 0; m < 4; ++m) { const float rs = __builtin_amdgcn_rsqf(st[ai * 4 + m] * (1.0f / 1024.0f) + eps);
; #pragma unroll
;                 for (int bj = 0; bj < 2; ++bj) { f32x4 v0 = acc[ai][bj][m][0] * rs, v1 = acc[ai][bj][m][1] * rs;
; #pragma unroll
;                     for (int k = 0; k < 4; ++k) { const float a = fmaxf(v0[k], 0.f), b = fmaxf(v1[k], 0.f); v0[k] = a * a; v1[k] = b * b; }
;                     po.put(bj, pack8(v0, v1)); }
;                 po.flush<true>(ai, m); }
;     }
	global_store_dwordx4 v[92:93], v[86:89], off offset:1024 nt
	v_mul_f32_e32 v82, v74, v74
	v_max_f32_e32 v74, 0, v79
	v_max_f32_e32 v75, 0, v75
	v_max_f32_e32 v76, 0, v76
	v_max_f32_e32 v78, 0, v78
	v_mul_f32_e32 v74, v74, v74
	v_mul_f32_e32 v79, v75, v75
	v_max_f32_e32 v75, 0, v80
	v_mul_f32_e32 v80, v76, v76
	v_max_f32_e32 v76, 0, v81
	v_max_f32_e32 v77, 0, v77
	v_mul_f32_e32 v78, v78, v78
	v_mul_f32_e32 v75, v75, v75
	v_mul_f32_e32 v76, v76, v76
	v_mul_f32_e32 v77, v77, v77
	v_cvt_pk_bf16_f32 v74, v78, v74
	v_max_f32_e32 v66, 0, v66
	v_max_f32_e32 v67, 0, v67
	v_max_f32_e32 v68, 0, v68
	v_cvt_pk_bf16_f32 v75, v75, v76
	v_cvt_pk_bf16_f32 v76, v82, v79
	v_cvt_pk_bf16_f32 v77, v80, v77
	ds_write_b128 v157, v[74:77]
	v_mul_f32_e32 v74, v66, v66
	v_max_f32_e32 v66, 0, v71
	v_mul_f32_e32 v71, v67, v67
	v_max_f32_e32 v67, 0, v72
	v_mul_f32_e32 v72, v68, v68
	v_max_f32_e32 v68, 0, v73
	v_max_f32_e32 v70, 0, v70
	v_mul_f32_e32 v66, v66, v66
	v_mul_f32_e32 v67, v67, v67
	v_max_f32_e32 v69, 0, v69
	v_mul_f32_e32 v68, v68, v68
	v_mul_f32_e32 v70, v70, v70
	v_mul_f32_e32 v69, v69, v69
	v_cvt_pk_bf16_f32 v66, v70, v66
	v_cvt_pk_bf16_f32 v67, v67, v68
	v_cvt_pk_bf16_f32 v68, v74, v71
	v_cvt_pk_bf16_f32 v69, v72, v69
	ds_write_b128 v157, v[66:69] offset:64
	ds_read_b128 v[66:69], v158
	ds_read_b128 v[70:73], v158 offset:1152
	s_waitcnt lgkmcnt(1)
	global_store_dwordx4 v[92:93], v[66:69], off offset:2048 nt
	s_waitcnt lgkmcnt(0)
	global_store_dwordx4 v[92:93], v[70:73], off offset:3072 nt
	v_max_f32_e32 v58, 0, v58
	v_mul_f32_e32 v66, v58, v58
	v_max_f32_e32 v58, 0, v63
	v_max_f32_e32 v59, 0, v59
	v_max_f32_e32 v60, 0, v60
	v_max_f32_e32 v62, 0, v62
	v_mul_f32_e32 v58, v58, v58
	v_mul_f32_e32 v63, v59, v59
	v_max_f32_e32 v59, 0, v64
	v_mul_f32_e32 v64, v60, v60
	v_max_f32_e32 v60, 0, v65
	v_max_f32_e32 v61, 0, v61
	v_mul_f32_e32 v62, v62, v62
	v_mul_f32_e32 v59, v59, v59
	v_mul_f32_e32 v60, v60, v60
	v_mul_f32_e32 v61, v61, v61
	v_cvt_pk_bf16_f32 v58, v62, v58
	v_max_f32_e32 v50, 0, v50
	v_max_f32_e32 v51, 0, v51
	v_max_f32_e32 v52, 0, v52
	v_cvt_pk_bf16_f32 v59, v59, v60
	v_cvt_pk_bf16_f32 v60, v66, v63
	v_cvt_pk_bf16_f32 v61, v64, v61
	ds_write_b128 v157, v[58:61]
	v_mul_f32_e32 v58, v50, v50
	v_max_f32_e32 v50, 0, v55
	v_mul_f32_e32 v55, v51, v51
	v_max_f32_e32 v51, 0, v56
	v_mul_f32_e32 v56, v52, v52
	v_max_f32_e32 v52, 0, v57
	v_max_f32_e32 v53, 0, v53
	v_max_f32_e32 v54, 0, v54
	v_mul_f32_e32 v50, v50, v50
	v_mul_f32_e32 v51, v51, v51
	v_mul_f32_e32 v52, v52, v52
	v_mul_f32_e32 v53, v53, v53
	v_mul_f32_e32 v54, v54, v54
	v_cvt_pk_bf16_f32 v50, v54, v50
	v_cvt_pk_bf16_f32 v51, v51, v52
	v_cvt_pk_bf16_f32 v52, v58, v55
	v_cvt_pk_bf16_f32 v53, v56, v53
	ds_write_b128 v157, v[50:53] offset:64
	ds_read_b128 v[50:53], v158
	ds_read_b128 v[54:57], v158 offset:1152
	v_add_co_u32_e32 v58, vcc, s47, v114
	s_nop 0
	s_nop 0
	v_addc_co_u32_e32 v59, vcc, 0, v115, vcc
	v_add_co_u32_e32 v62, vcc, s54, v114
	s_nop 0
	s_nop 0
	v_addc_co_u32_e32 v63, vcc, 0, v115, vcc
	v_max_f32_e32 v42, 0, v42
	s_waitcnt lgkmcnt(1)
	global_store_dwordx4 v[62:63], v[50:53], off offset:-4096 nt
	s_waitcnt lgkmcnt(0)
; __device__ __forceinline__ size_t tm_block(int pm, int ct, int nct) { return ((size_t)pm * nct + ct) * 32768; }
; __device__ __forceinline__ u32x4 pack8(const f32x4& v0, const f32x4& v1) { u32x4 w; w.x = cvt_pk_bf16(v0[0], v0[1]); w.y = cvt_pk_bf16(v0[2], v0[3]); w.z = cvt_pk_bf16(v1[0], v1[1]); w.w = cvt_pk_bf16(v1[2], v1[3]); return w; }
;     __device__ __forceinline__ void post(const f32x4 (&acc)[2][2][4][2], const float (&st)[8], const Unit& u, int wr, int wc, int fr, int fq) const {
;         const PieceOut po(scr, O, tm_block(u.pm, u.pn * 4 + wc, 64), wr, wc, fr, fq);
; #pragma unroll
;         for (int ai = 0; ai < 2; ++ai)
; #pragma unroll
;             for (int m = 0; m < 4; ++m) { const float rs = __builtin_amdgcn_rsqf(st[ai * 4 + m] * (1.0f / 1024.0f) + eps);
; #pragma unroll
;                 for (int bj = 0; bj < 2; ++bj) { f32x4 v0 = acc[ai][bj][m][0] * rs, v1 = acc[ai][bj][m][1] * rs;
; #pragma unroll
;                     for (int k = 0; k < 4; ++k) { const float a = fmaxf(v0[k], 0.f), b = fmaxf(v1[k], 0.f); v0[k] = a * a; v1[k] = b * b; }
;                     po.put(bj, pack8(v0, v1)); }
;                 po.flush<true>(ai, m); }
;     }
	global_store_dwordx4 v[58:59], v[54:57], off offset:1024 nt
	v_mul_f32_e32 v50, v42, v42
	v_max_f32_e32 v42, 0, v47
	v_max_f32_e32 v43, 0, v43
	v_max_f32_e32 v44, 0, v44
	v_max_f32_e32 v46, 0, v46
	v_mul_f32_e32 v42, v42, v42
	v_mul_f32_e32 v47, v43, v43
	v_max_f32_e32 v43, 0, v48
	v_mul_f32_e32 v48, v44, v44
	v_max_f32_e32 v44, 0, v49
	v_max_f32_e32 v45, 0, v45
	v_mul_f32_e32 v46, v46, v46
	v_mul_f32_e32 v43, v43, v43
	v_mul_f32_e32 v44, v44, v44
	v_mul_f32_e32 v45, v45, v45
	v_cvt_pk_bf16_f32 v42, v46, v42
	v_max_f32_e32 v34, 0, v34
	v_max_f32_e32 v35, 0, v35
	v_max_f32_e32 v36, 0, v36
	v_cvt_pk_bf16_f32 v43, v43, v44
	v_cvt_pk_bf16_f32 v44, v50, v47
	v_cvt_pk_bf16_f32 v45, v48, v45
	ds_write_b128 v157, v[42:45]
	v_mul_f32_e32 v42, v34, v34
	v_max_f32_e32 v34, 0, v39
	v_mul_f32_e32 v39, v35, v35
	v_max_f32_e32 v35, 0, v40
	v_mul_f32_e32 v40, v36, v36
	v_max_f32_e32 v36, 0, v41
	v_max_f32_e32 v38, 0, v38
	v_mul_f32_e32 v34, v34, v34
	v_mul_f32_e32 v35, v35, v35
	v_max_f32_e32 v37, 0, v37
	v_mul_f32_e32 v36, v36, v36
	v_mul_f32_e32 v38, v38, v38
	v_mul_f32_e32 v37, v37, v37
	v_cvt_pk_bf16_f32 v34, v38, v34
	v_cvt_pk_bf16_f32 v35, v35, v36
	v_cvt_pk_bf16_f32 v36, v42, v39
	v_cvt_pk_bf16_f32 v37, v40, v37
	ds_write_b128 v157, v[34:37] offset:64
	ds_read_b128 v[34:37], v158
	ds_read_b128 v[38:41], v158 offset:1152
	s_waitcnt lgkmcnt(1)
	global_store_dwordx4 v[58:59], v[34:37], off offset:2048 nt
	s_waitcnt lgkmcnt(0)
	global_store_dwordx4 v[58:59], v[38:41], off offset:3072 nt
	v_max_f32_e32 v26, 0, v26
	v_mul_f32_e32 v34, v26, v26
	v_max_f32_e32 v26, 0, v31
	v_max_f32_e32 v27, 0, v27
	v_max_f32_e32 v28, 0, v28
	v_max_f32_e32 v30, 0, v30
	v_mul_f32_e32 v26, v26, v26
	v_mul_f32_e32 v31, v27, v27
	v_max_f32_e32 v27, 0, v32
	v_mul_f32_e32 v32, v28, v28
	v_max_f32_e32 v28, 0, v33
	v_max_f32_e32 v29, 0, v29
	v_mul_f32_e32 v30, v30, v30
	v_mul_f32_e32 v27, v27, v27
	v_mul_f32_e32 v28, v28, v28
	v_mul_f32_e32 v29, v29, v29
	v_cvt_pk_bf16_f32 v26, v30, v26
	v_max_f32_e32 v18, 0, v18
	v_max_f32_e32 v19, 0, v19
	v_max_f32_e32 v20, 0, v20
	v_cvt_pk_bf16_f32 v27, v27, v28
	v_cvt_pk_bf16_f32 v28, v34, v31
	v_cvt_pk_bf16_f32 v29, v32, v29
	ds_write_b128 v157, v[26:29]
	v_mul_f32_e32 v26, v18, v18
	v_max_f32_e32 v18, 0, v23
	v_mul_f32_e32 v23, v19, v19
	v_max_f32_e32 v19, 0, v24
	v_mul_f32_e32 v24, v20, v20
	v_max_f32_e32 v20, 0, v25
	v_max_f32_e32 v22, 0, v22
	v_mul_f32_e32 v18, v18, v18
	v_mul_f32_e32 v19, v19, v19
	v_max_f32_e32 v21, 0, v21
	v_mul_f32_e32 v20, v20, v20
	v_mul_f32_e32 v22, v22, v22
	v_mul_f32_e32 v21, v21, v21
	v_cvt_pk_bf16_f32 v18, v22, v18
	v_cvt_pk_bf16_f32 v19, v19, v20
	v_cvt_pk_bf16_f32 v20, v26, v23
	v_cvt_pk_bf16_f32 v21, v24, v21
	ds_write_b128 v157, v[18:21] offset:64
	ds_read_b128 v[18:21], v158
	ds_read_b128 v[22:25], v158 offset:1152
	s_waitcnt lgkmcnt(1)
	global_store_dwordx4 v[62:63], v[18:21], off nt
	s_waitcnt lgkmcnt(0)
	global_store_dwordx4 v[62:63], v[22:25], off offset:1024 nt
	v_max_f32_e32 v10, 0, v10
	v_mul_f32_e32 v18, v10, v10
	v_max_f32_e32 v10, 0, v15
	v_max_f32_e32 v11, 0, v11
	v_max_f32_e32 v12, 0, v12
	v_max_f32_e32 v14, 0, v14
	v_mul_f32_e32 v10, v10, v10
	v_mul_f32_e32 v15, v11, v11
	v_max_f32_e32 v11, 0, v16
	v_mul_f32_e32 v16, v12, v12
	v_max_f32_e32 v12, 0, v17
	v_max_f32_e32 v13, 0, v13
	v_mul_f32_e32 v14, v14, v14
	v_mul_f32_e32 v11, v11, v11
	v_mul_f32_e32 v12, v12, v12
	v_mul_f32_e32 v13, v13, v13
	v_cvt_pk_bf16_f32 v10, v14, v10
	v_max_f32_e32 v2, 0, v2
	v_max_f32_e32 v3, 0, v3
	v_max_f32_e32 v4, 0, v4
	v_cvt_pk_bf16_f32 v11, v11, v12
	v_cvt_pk_bf16_f32 v12, v18, v15
	v_cvt_pk_bf16_f32 v13, v16, v13
	ds_write_b128 v157, v[10:13]
	v_mul_f32_e32 v10, v2, v2
	v_max_f32_e32 v2, 0, v7
	v_mul_f32_e32 v7, v3, v3
	v_max_f32_e32 v3, 0, v8
	v_mul_f32_e32 v8, v4, v4
	v_max_f32_e32 v4, 0, v9
	v_max_f32_e32 v5, 0, v5
	v_max_f32_e32 v6, 0, v6
	v_mul_f32_e32 v2, v2, v2
	v_mul_f32_e32 v3, v3, v3
	v_mul_f32_e32 v4, v4, v4
	v_mul_f32_e32 v5, v5, v5
	v_mul_f32_e32 v6, v6, v6
	v_cvt_pk_bf16_f32 v2, v6, v2
	v_cvt_pk_bf16_f32 v3, v3, v4
	v_cvt_pk_bf16_f32 v4, v10, v7
	v_cvt_pk_bf16_f32 v5, v8, v5
	ds_write_b128 v157, v[2:5] offset:64
	ds_read_b128 v[2:5], v158
	ds_read_b128 v[6:9], v158 offset:1152
	s_andn2_b64 vcc, exec, s[4:5]
	s_mov_b64 s[4:5], -1
	s_waitcnt lgkmcnt(1)
	global_store_dwordx4 v[62:63], v[2:5], off offset:2048 nt
	s_waitcnt lgkmcnt(0)
	global_store_dwordx4 v[62:63], v[6:9], off offset:3072 nt
	s_branch .Lp5_epi_join
